# GDN block forward substitution: the two independent chains (v-part, k-part) interleaved by hand, all LDS reads up front
# baseline (speedup 1.0000x reference)
.LBB0_403:
	v_lshrrev_b32_e32 v210, 3, v206
	v_mul_u32_u24_e32 v213, 0x90, v206
	s_add_i32 s12, 0, 0x1e600
	s_add_i32 s10, 0, 0x21e00
	v_or_b32_e32 v0, s86, v210
	v_xor_b32_e32 v0, v207, v0
	v_mul_u32_u24_e32 v187, 40, v206
	v_add3_u32 v187, s10, v208, v187
	v_add3_u32 v214, s12, v213, v209
	v_mul_lo_u32 v215, v118, s76
	v_mul_u32_u24_e32 v211, 0x440, v207
	v_lshlrev_b32_e32 v212, 1, v206
	v_add3_u32 v255, s95, v211, v212
	v_mov_b32_e32 v228, v0
	v_xor_b32_e32 v229, 4, v0
	v_xor_b32_e32 v230, 8, v0
	v_xor_b32_e32 v231, 12, v0
	v_lshl_add_u32 v228, v228, 3, v215
	v_lshl_add_u32 v229, v229, 3, v215
	v_lshl_add_u32 v230, v230, 3, v215
	v_lshl_add_u32 v231, v231, 3, v215
	v_add_u32_e32 v236, s65, v228
	v_add_u32_e32 v237, s65, v229
	v_add_u32_e32 v238, s65, v230
	v_add_u32_e32 v239, s65, v231
	s_waitcnt lgkmcnt(0)
	s_barrier
	ds_read_b64 v[124:125], v187
	ds_read_b64 v[148:149], v236
	ds_read_b64 v[154:155], v228 offset:34816
	ds_read_b64 v[150:151], v214 offset:2304
	ds_read_b64 v[142:143], v237
	ds_read_b64 v[156:157], v229 offset:34816
	ds_read_b64 v[126:127], v187 offset:640
	ds_read_b64 v[132:133], v214 offset:4608
	ds_read_b64 v[136:137], v214 offset:6912
	ds_read_b64 v[144:145], v238
	ds_read_b64 v[158:159], v230 offset:34816
	ds_read_b64 v[146:147], v239
	ds_read_b64 v[160:161], v231 offset:34816
	ds_read_b64 v[134:135], v214 offset:4640
	ds_read_b64 v[138:139], v214 offset:6944
	s_waitcnt lgkmcnt(12)
	v_mfma_f32_16x16x16_bf16 v[116:119], v[124:125], v[148:149], 0
	v_mfma_f32_16x16x16_bf16 v[162:165], v[124:125], v[154:155], 0
	ds_read_b64 v[128:129], v187 offset:1280
	ds_read_b64 v[130:131], v187 offset:1920
	ds_read_b64 v[152:153], v214 offset:6976
	s_waitcnt lgkmcnt(6)
	v_lshlrev_b32_e32 v108, 16, v142
	v_and_b32_e32 v109, 0xffff0000, v142
	v_lshlrev_b32_e32 v110, 16, v143
	v_and_b32_e32 v111, 0xffff0000, v143
	v_lshlrev_b32_e32 v166, 16, v156
	v_and_b32_e32 v167, 0xffff0000, v156
	v_lshlrev_b32_e32 v168, 16, v157
	v_and_b32_e32 v169, 0xffff0000, v157
	v_cvt_pk_bf16_f32 v170, v116, v117
	v_cvt_pk_bf16_f32 v171, v118, v119
	v_cvt_pk_bf16_f32 v236, v162, v163
	v_cvt_pk_bf16_f32 v237, v164, v165
	s_waitcnt lgkmcnt(3)
	v_lshlrev_b32_e32 v120, 16, v144
	v_and_b32_e32 v121, 0xffff0000, v144
	v_lshlrev_b32_e32 v122, 16, v145
	v_and_b32_e32 v123, 0xffff0000, v145
	v_lshlrev_b32_e32 v228, 16, v158
	v_and_b32_e32 v229, 0xffff0000, v158
	v_lshlrev_b32_e32 v230, 16, v159
	v_and_b32_e32 v231, 0xffff0000, v159
	v_mfma_f32_16x16x16_bf16 v[108:111], v[150:151], v[170:171], v[108:111]
	v_mfma_f32_16x16x16_bf16 v[166:169], v[150:151], v[236:237], v[166:169]
	v_lshlrev_b32_e32 v112, 16, v146
	v_and_b32_e32 v113, 0xffff0000, v146
	v_lshlrev_b32_e32 v114, 16, v147
	v_and_b32_e32 v115, 0xffff0000, v147
	v_lshlrev_b32_e32 v232, 16, v160
	v_and_b32_e32 v233, 0xffff0000, v160
	v_lshlrev_b32_e32 v234, 16, v161
	v_and_b32_e32 v235, 0xffff0000, v161
	v_mfma_f32_16x16x16_bf16 v[120:123], v[132:133], v[170:171], v[120:123]
	v_mfma_f32_16x16x16_bf16 v[228:231], v[132:133], v[236:237], v[228:231]
	v_mfma_f32_16x16x16_bf16 v[112:115], v[136:137], v[170:171], v[112:115]
	v_mfma_f32_16x16x16_bf16 v[232:235], v[136:137], v[236:237], v[232:235]
	v_cvt_pk_bf16_f32 v254, -v162, s0
	ds_write_b16 v255, v254 offset:0
	v_cvt_pk_bf16_f32 v254, -v163, s0
	ds_write_b16 v255, v254 offset:272
	v_cvt_pk_bf16_f32 v254, -v164, s0
	ds_write_b16 v255, v254 offset:544
	v_cvt_pk_bf16_f32 v254, -v165, s0
	ds_write_b16 v255, v254 offset:816
	v_cvt_pk_bf16_f32 v238, v108, v109
	v_cvt_pk_bf16_f32 v239, v110, v111
	v_cvt_pk_bf16_f32 v240, v166, v167
	v_cvt_pk_bf16_f32 v241, v168, v169
	s_nop 1
	v_mfma_f32_16x16x16_bf16 v[108:111], v[126:127], v[238:239], 0
	v_mfma_f32_16x16x16_bf16 v[166:169], v[126:127], v[240:241], 0
	s_nop 7
	v_cvt_pk_bf16_f32 v242, v108, v109
	v_cvt_pk_bf16_f32 v243, v110, v111
	v_cvt_pk_bf16_f32 v244, v166, v167
	v_cvt_pk_bf16_f32 v245, v168, v169
	s_nop 1
	v_mfma_f32_16x16x16_bf16 v[120:123], v[134:135], v[242:243], v[120:123]
	v_mfma_f32_16x16x16_bf16 v[228:231], v[134:135], v[244:245], v[228:231]
	v_mfma_f32_16x16x16_bf16 v[112:115], v[138:139], v[242:243], v[112:115]
	v_mfma_f32_16x16x16_bf16 v[232:235], v[138:139], v[244:245], v[232:235]
	v_cvt_pk_bf16_f32 v254, -v166, s0
	ds_write_b16 v255, v254 offset:4352
	v_cvt_pk_bf16_f32 v254, -v167, s0
	ds_write_b16 v255, v254 offset:4624
	v_cvt_pk_bf16_f32 v254, -v168, s0
	ds_write_b16 v255, v254 offset:4896
	v_cvt_pk_bf16_f32 v254, -v169, s0
	ds_write_b16 v255, v254 offset:5168
	v_cvt_pk_bf16_f32 v246, v120, v121
	v_cvt_pk_bf16_f32 v247, v122, v123
	v_cvt_pk_bf16_f32 v248, v228, v229
	v_cvt_pk_bf16_f32 v249, v230, v231
	s_waitcnt lgkmcnt(8)
	s_nop 0
	v_mfma_f32_16x16x16_bf16 v[120:123], v[128:129], v[246:247], 0
	v_mfma_f32_16x16x16_bf16 v[228:231], v[128:129], v[248:249], 0
	s_nop 7
	v_cvt_pk_bf16_f32 v250, v120, v121
	v_cvt_pk_bf16_f32 v251, v122, v123
	v_cvt_pk_bf16_f32 v252, v228, v229
	v_cvt_pk_bf16_f32 v253, v230, v231
	s_nop 1
	v_mfma_f32_16x16x16_bf16 v[112:115], v[152:153], v[250:251], v[112:115]
	v_mfma_f32_16x16x16_bf16 v[232:235], v[152:153], v[252:253], v[232:235]
	v_cvt_pk_bf16_f32 v254, -v228, s0
	ds_write_b16 v255, v254 offset:8704
	v_cvt_pk_bf16_f32 v254, -v229, s0
	ds_write_b16 v255, v254 offset:8976
	v_cvt_pk_bf16_f32 v254, -v230, s0
	ds_write_b16 v255, v254 offset:9248
	v_cvt_pk_bf16_f32 v254, -v231, s0
	ds_write_b16 v255, v254 offset:9520
	v_cvt_pk_bf16_f32 v238, v112, v113
	v_cvt_pk_bf16_f32 v239, v114, v115
	v_cvt_pk_bf16_f32 v240, v232, v233
	v_cvt_pk_bf16_f32 v241, v234, v235
	s_nop 1
	v_mfma_f32_16x16x16_bf16 v[112:115], v[130:131], v[238:239], 0
	v_mfma_f32_16x16x16_bf16 v[232:235], v[130:131], v[240:241], 0
	s_add_i32 s13, s94, 1
	s_nop 7
	v_cvt_pk_bf16_f32 v254, -v232, s0
	ds_write_b16 v255, v254 offset:13056
	v_cvt_pk_bf16_f32 v254, -v233, s0
	ds_write_b16 v255, v254 offset:13328
	v_cvt_pk_bf16_f32 v254, -v234, s0
	ds_write_b16 v255, v254 offset:13600
	v_cvt_pk_bf16_f32 v254, -v235, s0
	ds_write_b16 v255, v254 offset:13872
	s_cmp_lt_u32 s13, s85
	s_waitcnt lgkmcnt(0)
	s_barrier
	s_cbranch_scc0 .LBB0_409
	s_and_b64 vcc, exec, s[6:7]
	s_cbranch_vccnz .LBB0_409
	s_lshl_b32 s48, s13, 6
	v_add_u32_e32 v0, s48, v140
	v_xad_u32 v84, v0, -1, s80
	v_cndmask_b32_e64 v84, v84, v0, s[4:5]
	v_add_u32_e32 v0, 1, v0
	v_xad_u32 v85, v0, -1, s80
	v_cndmask_b32_e64 v0, v85, v0, s[4:5]
	v_min_i32_e32 v181, v84, v0
	v_add_u32_e32 v0, v181, v177
	v_mad_i64_i32 v[84:85], s[10:11], v0, s60, v[182:183]
	v_lshlrev_b32_e32 v0, 4, v205
	v_and_b32_e32 v0, 0xf0, v0
	v_lshl_add_u64 v[186:187], v[84:85], 0, v[0:1]
	s_and_b64 vcc, exec, s[6:7]
	s_mov_b64 s[10:11], -1
	s_cbranch_vccnz .LBB0_406
	v_add_u32_e32 v0, -2, v181
	v_cmp_gt_u32_e64 s[10:11], s43, v0
	v_add_u32_e32 v0, -1, v181
	s_nop 0
	v_cndmask_b32_e64 v85, 0, -1, s[10:11]
	v_cndmask_b32_e64 v84, 0, v192, s[10:11]
	v_lshl_add_u64 v[92:93], v[186:187], 0, v[84:85]
	global_load_dwordx4 v[84:87], v[92:93], off
	global_load_dwordx4 v[88:91], v[92:93], off offset:2048
	v_add_co_u32_e32 v92, vcc, 0x1000, v92
	s_waitcnt vmcnt(1)
	v_cndmask_b32_e64 v129, 0, v85, s[10:11]
	v_addc_co_u32_e32 v93, vcc, 0, v93, vcc
	global_load_dwordx4 v[92:95], v[92:93], off
	v_cmp_gt_u32_e32 vcc, s43, v0
	v_cndmask_b32_e64 v128, 0, v84, s[10:11]
	v_cndmask_b32_e64 v131, 0, v87, s[10:11]
	v_cndmask_b32_e64 v85, 0, -1, vcc
	v_cndmask_b32_e32 v84, 0, v193, vcc
	v_cndmask_b32_e64 v130, 0, v86, s[10:11]
	s_waitcnt vmcnt(1)
	v_cndmask_b32_e64 v127, 0, v91, s[10:11]
	v_cndmask_b32_e64 v126, 0, v90, s[10:11]
	v_cndmask_b32_e64 v125, 0, v89, s[10:11]
	v_cndmask_b32_e64 v124, 0, v88, s[10:11]
	v_add_u32_e32 v0, 1, v181
	s_waitcnt vmcnt(0)
	v_cndmask_b32_e64 v133, 0, v93, s[10:11]
	v_cndmask_b32_e64 v132, 0, v92, s[10:11]
	v_lshl_add_u64 v[92:93], v[186:187], 0, v[84:85]
	v_cndmask_b32_e64 v135, 0, v95, s[10:11]
	v_cndmask_b32_e64 v134, 0, v94, s[10:11]
	global_load_dwordx4 v[84:87], v[92:93], off
	global_load_dwordx4 v[88:91], v[92:93], off offset:2048
	v_add_co_u32_e64 v92, s[10:11], s59, v92
	s_waitcnt vmcnt(1)
	v_cndmask_b32_e32 v143, 0, v87, vcc
	v_addc_co_u32_e64 v93, s[10:11], 0, v93, s[10:11]
	global_load_dwordx4 v[92:95], v[92:93], off
	v_cndmask_b32_e32 v142, 0, v86, vcc
	v_cndmask_b32_e32 v141, 0, v85, vcc
	v_cndmask_b32_e32 v140, 0, v84, vcc
	s_waitcnt vmcnt(1)
	v_cndmask_b32_e32 v139, 0, v91, vcc
	v_cndmask_b32_e32 v138, 0, v90, vcc
	v_cndmask_b32_e32 v137, 0, v89, vcc
	v_cndmask_b32_e32 v136, 0, v88, vcc
	global_load_dwordx4 v[84:87], v[186:187], off
	global_load_dwordx4 v[88:91], v[186:187], off offset:2048
	s_waitcnt vmcnt(2)
	v_cndmask_b32_e32 v144, 0, v92, vcc
	v_add_co_u32_e64 v92, s[10:11], s59, v186
	v_cndmask_b32_e32 v145, 0, v93, vcc
	s_nop 0
	v_addc_co_u32_e64 v93, s[10:11], 0, v187, s[10:11]
	v_cndmask_b32_e32 v147, 0, v95, vcc
	v_cndmask_b32_e32 v146, 0, v94, vcc
	global_load_dwordx4 v[92:95], v[92:93], off
	v_cmp_gt_u32_e32 vcc, s43, v181
	s_waitcnt vmcnt(2)
	s_nop 0
	v_cndmask_b32_e32 v87, 0, v87, vcc
	v_cndmask_b32_e32 v86, 0, v86, vcc
	v_cndmask_b32_e32 v85, 0, v85, vcc
	v_cndmask_b32_e32 v84, 0, v84, vcc
	s_waitcnt vmcnt(1)
	v_cndmask_b32_e32 v91, 0, v91, vcc
	v_cndmask_b32_e32 v90, 0, v90, vcc
	v_cndmask_b32_e32 v89, 0, v89, vcc
	v_cndmask_b32_e32 v88, 0, v88, vcc
	s_waitcnt vmcnt(0)
	v_cndmask_b32_e32 v95, 0, v95, vcc
	v_cndmask_b32_e32 v94, 0, v94, vcc
	v_cndmask_b32_e32 v93, 0, v93, vcc
	v_cndmask_b32_e32 v92, 0, v92, vcc
	v_cmp_gt_u32_e32 vcc, s43, v0
	s_nop 1
	v_cndmask_b32_e32 v0, 0, v194, vcc
	v_lshl_add_u64 v[104:105], v[186:187], 0, v[0:1]
	global_load_dwordx4 v[96:99], v[104:105], off
	global_load_dwordx4 v[100:103], v[104:105], off offset:2048
	v_add_co_u32_e64 v104, s[10:11], s59, v104
	v_add_u32_e32 v0, 2, v181
	s_nop 0
	v_addc_co_u32_e64 v105, s[10:11], 0, v105, s[10:11]
	global_load_dwordx4 v[104:107], v[104:105], off
	s_waitcnt vmcnt(2)
	v_cndmask_b32_e32 v99, 0, v99, vcc
	v_cndmask_b32_e32 v98, 0, v98, vcc
	v_cndmask_b32_e32 v97, 0, v97, vcc
	v_cndmask_b32_e32 v96, 0, v96, vcc
	s_waitcnt vmcnt(1)
	v_cndmask_b32_e32 v103, 0, v103, vcc
	v_cndmask_b32_e32 v102, 0, v102, vcc
	v_cndmask_b32_e32 v101, 0, v101, vcc
	v_cndmask_b32_e32 v100, 0, v100, vcc
	s_waitcnt vmcnt(0)
	v_cndmask_b32_e32 v107, 0, v107, vcc
	v_cndmask_b32_e32 v106, 0, v106, vcc
	v_cndmask_b32_e32 v105, 0, v105, vcc
	v_cndmask_b32_e32 v104, 0, v104, vcc
	v_cmp_gt_u32_e32 vcc, s43, v0
	s_nop 1
	v_cndmask_b32_e32 v0, 0, v195, vcc
	v_lshl_add_u64 v[156:157], v[186:187], 0, v[0:1]
	global_load_dwordx4 v[148:151], v[156:157], off
	global_load_dwordx4 v[152:155], v[156:157], off offset:2048
	v_add_co_u32_e64 v156, s[10:11], s59, v156
	v_add_u32_e32 v0, 3, v181
	s_nop 0
	v_addc_co_u32_e64 v157, s[10:11], 0, v157, s[10:11]
	global_load_dwordx4 v[160:163], v[156:157], off
	s_waitcnt vmcnt(2)
	v_cndmask_b32_e32 v159, 0, v151, vcc
	v_cndmask_b32_e32 v158, 0, v150, vcc
	v_cndmask_b32_e32 v157, 0, v149, vcc
	v_cndmask_b32_e32 v156, 0, v148, vcc
	s_waitcnt vmcnt(1)
	v_cndmask_b32_e32 v155, 0, v155, vcc
	v_cndmask_b32_e32 v154, 0, v154, vcc
	v_cndmask_b32_e32 v153, 0, v153, vcc
	v_cndmask_b32_e32 v152, 0, v152, vcc
	s_waitcnt vmcnt(0)
	v_cndmask_b32_e32 v151, 0, v163, vcc
	v_cndmask_b32_e32 v150, 0, v162, vcc
	v_cndmask_b32_e32 v149, 0, v161, vcc
	v_cndmask_b32_e32 v148, 0, v160, vcc
	v_cmp_gt_u32_e32 vcc, s43, v0
	s_nop 1
	v_cndmask_b32_e32 v0, 0, v196, vcc
	v_lshl_add_u64 v[160:161], v[186:187], 0, v[0:1]
	global_load_dwordx4 v[168:171], v[160:161], off
	global_load_dwordx4 v[164:167], v[160:161], off offset:2048
	v_add_co_u32_e64 v160, s[10:11], s59, v160
	s_waitcnt vmcnt(1)
	v_cndmask_b32_e32 v171, 0, v171, vcc
	v_addc_co_u32_e64 v161, s[10:11], 0, v161, s[10:11]
	global_load_dwordx4 v[160:163], v[160:161], off
	v_cndmask_b32_e32 v170, 0, v170, vcc
	v_cndmask_b32_e32 v169, 0, v169, vcc
	v_cndmask_b32_e32 v168, 0, v168, vcc
	s_waitcnt vmcnt(1)
	v_cndmask_b32_e32 v167, 0, v167, vcc
	v_cndmask_b32_e32 v166, 0, v166, vcc
	v_cndmask_b32_e32 v165, 0, v165, vcc
	v_cndmask_b32_e32 v164, 0, v164, vcc
	s_mov_b64 s[10:11], 0
	s_waitcnt vmcnt(0)
	v_cndmask_b32_e32 v163, 0, v163, vcc
	v_cndmask_b32_e32 v162, 0, v162, vcc
	v_cndmask_b32_e32 v161, 0, v161, vcc
	v_cndmask_b32_e32 v160, 0, v160, vcc
